# NA fixed-softmax loop: 24 per-read bias address adds folded into DS offset fields
# speedup vs baseline: 1.0087x; 1.0079x over previous
.LBB0_1250:
	s_andn2_b64 vcc, exec, s[0:1]
	s_cbranch_vccnz .LBB0_1267
	s_and_b64 vcc, exec, s[2:3]
	s_cbranch_vccnz .LBB0_1267
	s_add_u32 s0, s94, 0x17600000
	v_writelane_b32 v254, s0, 34
	s_addc_u32 s0, s95, 0
	v_writelane_b32 v254, s0, 36
	s_add_u32 s0, s94, 0x19600000
	s_addc_u32 s1, s95, 0
	v_lshrrev_b32_e32 v1, 5, v158
	v_and_b32_e32 v2, 7, v160
	v_lshrrev_b32_e32 v8, 4, v158
	v_lshrrev_b32_e32 v13, 1, v158
	v_lshlrev_b32_e32 v9, 1, v158
	v_writelane_b32 v254, s0, 37
	v_lshlrev_b32_e32 v4, 4, v1
	v_mov_b32_e32 v5, v149
	v_bitop3_b32 v10, v8, v160, 7 bitop3:0x78
	v_bitop3_b32 v11, v8, v2, 4 bitop3:0x36
	v_bitop3_b32 v12, v8, v160, 3 bitop3:0x78
	v_and_b32_e32 v8, 19, v160
	v_and_b32_e32 v9, 8, v9
	v_and_b32_e32 v15, 4, v13
	v_writelane_b32 v254, s1, 38
	v_and_b32_e32 v144, 31, v160
	v_lshl_add_u64 v[6:7], s[94:95], 0, v[4:5]
	s_mov_b64 s[0:1], 0x15600000
	v_or3_b32 v8, v8, v9, v15
	v_lshl_add_u64 v[146:147], v[6:7], 0, s[0:1]
	v_or_b32_e32 v162, 32, v158
	v_cmp_gt_u32_e64 s[0:1], 16, v144
	v_lshlrev_b32_e32 v8, 10, v8
	v_mov_b32_e32 v9, v149
	v_lshlrev_b32_e32 v148, 3, v1
	v_writelane_b32 v254, s0, 39
	v_lshl_add_u64 v[8:9], s[94:95], 0, v[8:9]
	v_add_u32_e32 v16, -8, v162
	v_writelane_b32 v254, s1, 40
	v_lshl_add_u64 v[4:5], v[8:9], 0, v[4:5]
	s_mov_b64 s[0:1], 0xd4400
	v_min_u32_e32 v16, 48, v16
	v_or_b32_e32 v18, 32, v148
	v_bfe_u32 v3, v160, 3, 2
	v_lshl_add_u64 v[160:161], v[4:5], 0, s[0:1]
	s_mov_b64 s[0:1], 0xd8400
	v_sub_u32_e32 v17, v148, v16
	v_sub_u32_e32 v16, v18, v16
	v_lshl_add_u64 v[164:165], v[6:7], 0, s[0:1]
	v_cmp_gt_u32_e64 s[0:1], 16, v16
	v_sub_u32_e64 v8, v144, 8 clamp
	v_sub_u32_e32 v9, v148, v8
	v_writelane_b32 v254, s0, 41
	v_add_u32_e32 v21, 1, v9
	v_sub_u32_e32 v8, v18, v8
	v_writelane_b32 v254, s1, 42
	s_movk_i32 s0, 0xffef
	v_cmp_lt_u32_e64 s[2:3], s0, v17
	v_cmp_lt_u32_e64 s[6:7], s0, v9
	s_mov_b32 s15, s49
	v_writelane_b32 v254, s2, 43
	v_cmp_gt_u32_e64 s[60:61], 16, v8
	v_cmp_gt_u32_e64 s[62:63], 15, v8
	v_writelane_b32 v254, s3, 44
	v_cmp_gt_u32_e64 s[2:3], 16, v9
	v_cmp_gt_u32_e64 s[64:65], 14, v8
	v_cmp_gt_u32_e64 s[66:67], 13, v8
	v_writelane_b32 v254, s2, 45
	v_cmp_gt_u32_e64 s[68:69], 12, v8
	v_cmp_gt_u32_e64 s[70:71], 11, v8
	v_writelane_b32 v254, s3, 46
	v_cmp_gt_u32_e64 s[2:3], 16, v21
	v_add_u32_e32 v21, 2, v9
	v_cmp_gt_u32_e64 s[72:73], 10, v8
	v_writelane_b32 v254, s2, 47
	v_add_u32_e32 v8, 1, v16
	v_cmp_gt_u32_e64 s[74:75], 16, v8
	v_writelane_b32 v254, s3, 48
	v_cmp_gt_u32_e64 s[2:3], 16, v21
	v_add_u32_e32 v21, 3, v9
	v_add_u32_e32 v8, 2, v16
	v_writelane_b32 v254, s2, 49
	v_lshrrev_b32_e32 v145, 2, v158
	v_cmp_gt_u32_e64 s[76:77], 16, v8
	v_writelane_b32 v254, s3, 50
	v_cmp_gt_u32_e64 s[2:3], 16, v21
	v_add_u32_e32 v21, 4, v9
	v_cmp_gt_u32_e64 s[20:21], 16, v21
	v_add_u32_e32 v21, 5, v9
	v_cmp_gt_u32_e64 s[22:23], 16, v21
	v_add_u32_e32 v21, 6, v9
	v_cmp_gt_u32_e64 s[24:25], 16, v21
	v_add_u32_e32 v21, 7, v9
	v_cmp_gt_u32_e64 s[26:27], 16, v21
	v_add_u32_e32 v21, 17, v9
	v_cmp_gt_u32_e64 s[30:31], 16, v21
	v_add_u32_e32 v21, 18, v9
	v_cmp_gt_u32_e64 s[34:35], 16, v21
	v_add_u32_e32 v21, 19, v9
	v_cmp_gt_u32_e64 s[36:37], 16, v21
	v_add_u32_e32 v21, 20, v9
	v_cmp_gt_u32_e64 s[38:39], 16, v21
	v_add_u32_e32 v21, 21, v9
	v_cmp_gt_u32_e64 s[40:41], 16, v21
	v_add_u32_e32 v21, 22, v9
	v_add_u32_e32 v9, 23, v9
	v_cmp_gt_u32_e64 s[44:45], 16, v9
	v_add_u32_e32 v9, 17, v17
	v_cmp_gt_u32_e64 s[46:47], 16, v9
	v_add_u32_e32 v9, 18, v17
	v_cmp_gt_u32_e64 s[48:49], 16, v9
	v_add_u32_e32 v9, 19, v17
	v_cmp_gt_u32_e64 s[50:51], 16, v9
	v_add_u32_e32 v9, 20, v17
	v_cmp_gt_u32_e64 s[52:53], 16, v9
	v_add_u32_e32 v9, 21, v17
	v_add_u32_e32 v8, 3, v16
	v_and_or_b32 v0, v145, 8, v3
	v_bfe_u32 v14, v158, 1, 3
	v_bfe_u32 v5, v158, 2, 2
	v_cmp_gt_u32_e64 s[54:55], 16, v9
	v_add_u32_e32 v9, 22, v17
	v_cmp_gt_u32_e64 s[78:79], 16, v8
	v_add_u32_e32 v8, 4, v16
	v_lshlrev_b32_e32 v3, 10, v3
	v_bitop3_b32 v13, v13, v1, 7 bitop3:0x6c
	v_bitop3_b32 v18, v1, v14, 2 bitop3:0x36
	v_bitop3_b32 v19, v1, v14, 4 bitop3:0x36
	v_bitop3_b32 v14, v1, v14, 6 bitop3:0x36
	v_bitop3_b32 v20, v145, v1, 3 bitop3:0x6c
	v_bitop3_b32 v5, v1, v5, 2 bitop3:0x36
	v_cmp_gt_u32_e64 s[56:57], 16, v9
	v_add_u32_e32 v9, 23, v17
	v_cmp_gt_u32_e64 s[80:81], 16, v8
	v_add_u32_e32 v8, 5, v16
	v_lshl_or_b32 v1, v1, 13, v3
	v_cmp_gt_u32_e64 s[58:59], 16, v9
	v_cmp_gt_u32_e64 s[82:83], 16, v8
	v_lshl_add_u64 v[8:9], s[94:95], 0, v[148:149]
	v_lshl_or_b32 v148, v10, 4, v1
	v_writelane_b32 v254, s2, 51
	v_add_u32_e32 v17, 6, v16
	v_lshl_add_u64 v[168:169], s[86:87], 0, v[148:149]
	v_lshl_or_b32 v148, v11, 4, v1
	v_lshlrev_b32_e32 v3, 2, v162
	v_lshlrev_b32_e32 v0, 9, v0
	v_lshlrev_b32_e32 v2, 3, v12
	v_lshlrev_b32_e32 v4, 3, v10
	v_lshlrev_b32_e32 v6, 3, v11
	v_lshl_add_u32 v7, v144, 7, s33
	v_lshl_add_u32 v15, v144, 6, s33
	v_lshlrev_b32_e32 v13, 4, v13
	v_lshlrev_b32_e32 v18, 4, v18
	v_lshlrev_b32_e32 v19, 4, v19
	v_lshlrev_b32_e32 v14, 4, v14
	v_lshlrev_b32_e32 v20, 4, v20
	v_lshlrev_b32_e32 v5, 4, v5
	v_writelane_b32 v254, s3, 52
	v_cmp_gt_u32_e64 s[42:43], 16, v21
	v_cmp_gt_u32_e64 s[84:85], 16, v17
	v_add_u32_e32 v17, 7, v16
	v_add_u32_e32 v21, 17, v16
	v_add_u32_e32 v22, 18, v16
	v_add_u32_e32 v23, 19, v16
	v_add_u32_e32 v24, 20, v16
	v_add_u32_e32 v25, 21, v16
	v_add_u32_e32 v26, 22, v16
	v_add_u32_e32 v27, 23, v16
	s_mov_b64 s[0:1], 0x5600000
	v_lshl_add_u64 v[170:171], s[86:87], 0, v[148:149]
	v_lshlrev_b32_e32 v148, 4, v12
	v_lshlrev_b32_e32 v1, 15, v145
	v_sub_u32_e32 v219, 0, v3
	v_lshlrev_b32_e32 v3, 2, v144
	v_lshl_add_u64 v[166:167], v[8:9], 0, s[0:1]
	v_lshl_add_u64 v[172:173], s[86:87], 0, v[148:149]
	v_and_b32_e32 v163, 32, v158
	v_add_u32_e32 v163, 0x202b0, v163
	v_sub_u32_e32 v220, 0, v3
	v_lshlrev_b32_e32 v221, 1, v1
	v_lshlrev_b32_e32 v158, 1, v2
	v_lshlrev_b32_e32 v174, 1, v0
	v_lshlrev_b32_e32 v176, 1, v4
	v_lshlrev_b32_e32 v178, 1, v6
	v_add_u32_e32 v222, v7, v13
	v_add_u32_e32 v223, v7, v18
	v_add_u32_e32 v224, v7, v19
	v_add_u32_e32 v225, v7, v14
	v_add_u32_e32 v226, v15, v20
	v_add_u32_e32 v227, v15, v5
	v_writelane_b32 v254, s18, 53
	v_cmp_gt_u32_e64 s[86:87], 16, v17
	v_cmp_lt_u32_e64 s[88:89], 23, v16
	v_cmp_gt_u32_e64 s[90:91], 16, v21
	v_cmp_gt_u32_e64 s[92:93], 16, v22
	v_cmp_gt_u32_e64 s[94:95], 16, v23
	v_cmp_gt_u32_e64 s[96:97], 16, v24
	v_cmp_gt_u32_e64 s[2:3], 16, v25
	v_cmp_gt_u32_e64 s[4:5], 16, v26
	v_cmp_gt_u32_e64 s[0:1], 16, v27
	s_branch .LBB0_1254

.LBB0_1263:
	v_add_f32_e32 v64, 0, v148
	v_add_f32_e32 v65, 0, v177
	v_add_f32_e32 v64, v64, v179
	v_add_f32_e32 v65, v65, v202
	v_add_f32_e32 v64, v64, v203
	v_add_f32_e32 v65, v65, v204
	v_add_f32_e32 v148, v64, v205
	v_add_f32_e32 v64, v65, v230
	v_mov_b32_e32 v65, v149
	v_pk_add_f32 v[66:67], v[148:149], v[74:75]
	v_pk_add_f32 v[64:65], v[64:65], v[72:73]
	v_pk_add_f32 v[66:67], v[66:67], v[68:69]
	v_pk_add_f32 v[64:65], v[64:65], v[70:71]
	v_pk_add_f32 v[66:67], v[66:67], v[78:79]
	v_pk_add_f32 v[64:65], v[64:65], v[198:199]
	v_pk_add_f32 v[66:67], v[66:67], v[76:77]
	v_pk_add_f32 v[64:65], v[64:65], v[200:201]
	v_readlane_b32 s14, v254, 41
	v_pk_add_f32 v[64:65], v[66:67], v[64:65]
	v_readlane_b32 s15, v254, 42
	v_pk_add_f32 v[190:191], v[190:191], v[64:65]
	v_mfma_f32_32x32x16_bf16 v[64:79], v[140:143], v[96:99], 0
	s_add_i32 s12, s12, 2
	v_add_u32_e32 v233, 0x80, v233
	v_add_u32_e32 v228, 0x7c, v228
	v_add_u32_e32 v229, 0x7c, v229
	s_andn2_b64 vcc, exec, s[8:9]
	s_waitcnt lgkmcnt(0)
	v_mfma_f32_32x32x16_bf16 v[64:79], v[136:139], v[100:103], v[64:79]
	v_mfma_f32_32x32x16_bf16 v[64:79], v[128:131], v[104:107], v[64:79]
	v_mfma_f32_32x32x16_bf16 v[64:79], v[132:135], v[108:111], v[64:79]
	s_nop 11
	ds_read2_b32 v[72:73], v175 offset0:32 offset1:33
	s_waitcnt lgkmcnt(0)
	v_add_f32_e32 v64, v64, v72
	v_cndmask_b32_e64 v71, v216, v64, s[60:61]
	v_add_f32_e32 v64, v65, v73
	v_cndmask_b32_e64 v72, v216, v64, s[62:63]
	ds_read2_b32 v[64:65], v175 offset0:34 offset1:35
	v_exp_f32_e32 v194, v71
	v_exp_f32_e32 v192, v72
	s_waitcnt lgkmcnt(0)
	v_add_f32_e32 v64, v66, v64
	v_cndmask_b32_e64 v66, v216, v64, s[64:65]
	v_add_f32_e32 v64, v67, v65
	v_cndmask_b32_e64 v67, v216, v64, s[66:67]
	ds_read2_b32 v[64:65], v175 offset0:36 offset1:37
	v_exp_f32_e32 v198, v66
	v_exp_f32_e32 v196, v67
	s_waitcnt lgkmcnt(0)
	v_add_f32_e32 v64, v68, v64
	ds_read_b32 v68, v175 offset:152
	v_add_f32_e32 v65, v69, v65
	v_cndmask_b32_e64 v64, v216, v64, s[68:69]
	v_cndmask_b32_e64 v65, v216, v65, s[70:71]
	v_exp_f32_e32 v202, v64
	s_waitcnt lgkmcnt(0)
	v_add_f32_e32 v68, v70, v68
	v_cndmask_b32_e64 v68, v216, v68, s[72:73]
	v_exp_f32_e32 v200, v65
	v_exp_f32_e32 v204, v68
	v_mfma_f32_32x32x16_bf16 v[64:79], v[140:143], v[112:115], 0
	v_mfma_f32_32x32x16_bf16 v[64:79], v[136:139], v[116:119], v[64:79]
	v_mfma_f32_32x32x16_bf16 v[64:79], v[128:131], v[120:123], v[64:79]
	ds_read2_b32 v[128:129], v159 offset0:32 offset1:33
	v_mfma_f32_32x32x16_bf16 v[64:79], v[132:135], v[124:127], v[64:79]
	s_waitcnt lgkmcnt(0)
	s_nop 10
	v_add_f32_e32 v64, v64, v128
	v_cndmask_b32_e64 v128, v216, v64, s[14:15]
	v_add_f32_e32 v64, v65, v129
	v_cndmask_b32_e64 v129, v216, v64, s[74:75]
	ds_read2_b32 v[64:65], v159 offset0:34 offset1:35
	v_add_u32_e32 v231, 0x10000, v231
	v_add_u32_e32 v232, 0x10000, v232
	s_waitcnt lgkmcnt(0)
	v_add_f32_e32 v64, v66, v64
	v_cndmask_b32_e64 v66, v216, v64, s[76:77]
	v_add_f32_e32 v64, v67, v65
	v_cndmask_b32_e64 v67, v216, v64, s[78:79]
	ds_read2_b32 v[64:65], v159 offset0:36 offset1:37
	v_exp_f32_e32 v130, v66
	v_exp_f32_e32 v131, v67
	s_waitcnt lgkmcnt(0)
	v_add_f32_e32 v64, v68, v64
	v_cndmask_b32_e64 v68, v216, v64, s[80:81]
	v_add_f32_e32 v64, v69, v65
	v_cndmask_b32_e64 v69, v216, v64, s[82:83]
	ds_read2_b32 v[64:65], v159 offset0:38 offset1:39
	s_waitcnt lgkmcnt(0)
	v_add_f32_e32 v64, v70, v64
	v_cndmask_b32_e64 v70, v216, v64, s[84:85]
	v_add_f32_e32 v64, v71, v65
	v_cndmask_b32_e64 v71, v216, v64, s[86:87]
	ds_read2_b32 v[64:65], v159 offset0:48 offset1:49
	v_exp_f32_e32 v132, v70
	v_exp_f32_e32 v133, v71
	v_mov_b32_e32 v70, v149
	s_waitcnt lgkmcnt(0)
	v_add_f32_e32 v64, v72, v64
	v_cndmask_b32_e64 v72, v216, v64, s[88:89]
	v_add_f32_e32 v64, v73, v65
	v_cndmask_b32_e64 v73, v216, v64, s[90:91]
	ds_read2_b32 v[64:65], v159 offset0:50 offset1:51
	v_exp_f32_e32 v72, v72
	v_exp_f32_e32 v195, v73
	s_waitcnt lgkmcnt(0)
	v_add_f32_e32 v64, v74, v64
	v_cndmask_b32_e64 v74, v216, v64, s[92:93]
	v_add_f32_e32 v64, v75, v65
	v_cndmask_b32_e64 v75, v216, v64, s[94:95]
	ds_read2_b32 v[64:65], v159 offset0:52 offset1:53
	v_exp_f32_e32 v193, v74
	v_exp_f32_e32 v199, v75
	s_waitcnt lgkmcnt(0)
	v_add_f32_e32 v64, v76, v64
	v_cndmask_b32_e64 v76, v216, v64, s[96:97]
	v_add_f32_e32 v64, v77, v65
	v_cndmask_b32_e64 v77, v216, v64, s[2:3]
	ds_read2_b32 v[64:65], v159 offset0:54 offset1:55
	v_exp_f32_e32 v197, v76
	v_exp_f32_e32 v203, v77
	s_waitcnt lgkmcnt(0)
	v_add_f32_e32 v64, v78, v64
	v_exp_f32_e32 v78, v128
	v_add_f32_e32 v65, v79, v65
	v_exp_f32_e32 v79, v129
	v_cndmask_b32_e64 v64, v216, v64, s[4:5]
	v_add_f32_e32 v128, 0, v78
	v_add_f32_e32 v66, v128, v130
	v_add_f32_e32 v129, 0, v79
	v_exp_f32_e32 v128, v68
	v_add_f32_e32 v67, v129, v131
	v_exp_f32_e32 v129, v69
	v_cndmask_b32_e64 v65, v216, v65, s[0:1]
	v_add_f32_e32 v66, v66, v128
	v_add_f32_e32 v66, v66, v132
	v_add_f32_e32 v67, v67, v129
	v_add_f32_e32 v69, v67, v133
	v_add_f32_e32 v71, v66, v72
	v_exp_f32_e32 v201, v64
	v_exp_f32_e32 v205, v65
	v_cvt_pk_bf16_f32 v64, v194, v192
	v_cvt_pk_bf16_f32 v65, v198, v196
	v_cvt_pk_bf16_f32 v66, v202, v200
	v_cvt_pk_bf16_f32 v67, v204, 0
	v_mov_b32_e32 v68, v149
	v_pk_add_f32 v[68:69], v[68:69], v[194:195]
	v_mfma_f32_32x32x16_bf16 v[32:47], v[92:95], v[64:67], v[32:47]
	v_add_f32_e64 v70, v70, v192
	v_add_f32_e64 v71, v71, v193
	v_add_f32_e64 v68, v68, v198
	v_add_f32_e64 v69, v69, v199
	v_add_f32_e64 v70, v70, v196
	v_add_f32_e64 v71, v71, v197
	v_pk_add_f32 v[68:69], v[68:69], v[202:203]
	v_pk_add_f32 v[70:71], v[70:71], v[200:201]
	v_pk_add_f32 v[68:69], v[68:69], v[204:205]
	v_mfma_f32_32x32x16_bf16 v[48:63], v[88:91], v[64:67], v[48:63]
	v_cvt_pk_bf16_f32 v64, v78, v79
	v_cvt_pk_bf16_f32 v65, v130, v131
	v_cvt_pk_bf16_f32 v66, v128, v129
	v_cvt_pk_bf16_f32 v67, v132, v133
	v_add_f32_e64 v68, v70, v68
	v_add_f32_e64 v69, v71, v69
	v_pk_add_f32 v[190:191], v[190:191], v[68:69]
	v_mfma_f32_32x32x16_bf16 v[0:15], v[92:95], v[64:67], v[0:15]
	v_mfma_f32_32x32x16_bf16 v[16:31], v[88:91], v[64:67], v[16:31]
	v_cvt_pk_bf16_f32 v64, v72, v195
	v_cvt_pk_bf16_f32 v65, v193, v199
	v_cvt_pk_bf16_f32 v66, v197, v203
	v_cvt_pk_bf16_f32 v67, v201, v205
	s_nop 1
	v_mfma_f32_32x32x16_bf16 v[0:15], v[84:87], v[64:67], v[0:15]
	v_mfma_f32_32x32x16_bf16 v[16:31], v[80:83], v[64:67], v[16:31]
	s_cbranch_vccz .LBB0_1253
.LBB0_1264:
	s_waitcnt vmcnt(0)
	ds_read_b128 v[80:83], v222
	ds_read_b128 v[136:139], v223
	ds_read_b128 v[132:135], v224
	ds_read_b128 v[128:131], v225
	ds_read_b128 v[84:87], v226 offset:4096
	s_add_i32 m0, s33, 0x2000
	s_add_u32 s98, s32, 0x17608000
	s_addc_u32 s99, s100, 0
	global_load_lds_dwordx4 v231, s[98:99]
	s_add_i32 m0, s33, 0x2400
	s_add_u32 s98, s32, 0x17609000
	s_addc_u32 s99, s100, 0
	global_load_lds_dwordx4 v232, s[98:99]
	s_add_i32 m0, s33, 0x2800
	s_add_u32 s98, s32, 0x1760c000
	s_addc_u32 s99, s100, 0
	global_load_lds_dwordx4 v231, s[98:99]
	s_add_i32 m0, s33, 0x2c00
	s_add_u32 s98, s32, 0x1760d000
	s_addc_u32 s99, s100, 0
	global_load_lds_dwordx4 v232, s[98:99]
	s_add_i32 m0, s33, 0x3000
	s_add_u32 s98, s32, 0x15600040
	s_addc_u32 s99, s100, 0
	global_load_lds_dwordx4 v233, s[98:99]
	s_add_i32 m0, s33, 0x3400
	s_add_u32 s98, s32, 0x15700040
	s_addc_u32 s99, s100, 0
	global_load_lds_dwordx4 v233, s[98:99]
	s_add_i32 m0, s33, 0x3800
	s_add_u32 s98, s32, 0x15800040
	s_addc_u32 s99, s100, 0
	global_load_lds_dwordx4 v233, s[98:99]
	s_add_i32 m0, s33, 0x3c00
	s_add_u32 s98, s32, 0x15900040
	s_addc_u32 s99, s100, 0
	global_load_lds_dwordx4 v233, s[98:99]
	s_waitcnt lgkmcnt(0)
	v_mfma_f32_32x32x16_bf16 v[64:79], v[80:83], v[96:99], 0
	v_mfma_f32_32x32x16_bf16 v[64:79], v[136:139], v[100:103], v[64:79]
	v_mfma_f32_32x32x16_bf16 v[64:79], v[132:135], v[104:107], v[64:79]
	v_mfma_f32_32x32x16_bf16 v[64:79], v[128:131], v[108:111], v[64:79]
	v_add_u32_e32 v175, v229, v163
	ds_read2_b32 v[88:89], v175 offset0:0 offset1:1
	ds_read2_b32 v[90:91], v175 offset0:2 offset1:3
	v_readlane_b32 s8, v254, 45
	v_readlane_b32 s9, v254, 46
	s_waitcnt lgkmcnt(0)
	s_nop 4
	v_add_f32_e32 v64, v64, v88
	v_add_u32_e32 v159, v228, v163
	v_cndmask_b32_e64 v88, v216, v64, s[8:9]
	v_readlane_b32 s8, v254, 47
	v_add_f32_e32 v64, v65, v89
	v_readlane_b32 s9, v254, 48
	v_exp_f32_e32 v148, v88
	s_cmp_gt_u32 s12, 13
	v_cndmask_b32_e64 v89, v216, v64, s[8:9]
	v_readlane_b32 s8, v254, 49
	v_add_f32_e32 v64, v66, v90
	v_readlane_b32 s9, v254, 50
	v_add_f32_e32 v66, v67, v91
	v_exp_f32_e32 v177, v89
	v_cndmask_b32_e64 v90, v216, v64, s[8:9]
	v_readlane_b32 s8, v254, 51
	v_readlane_b32 s9, v254, 52
	ds_read2_b32 v[64:65], v175 offset0:4 offset1:5
	v_cndmask_b32_e64 v91, v216, v66, s[8:9]
	ds_read2_b32 v[66:67], v175 offset0:6 offset1:7
	v_exp_f32_e32 v179, v90
	s_waitcnt lgkmcnt(0)
	v_add_f32_e32 v64, v68, v64
	v_add_f32_e32 v65, v69, v65
	v_cndmask_b32_e64 v64, v216, v64, s[20:21]
	v_add_f32_e32 v66, v70, v66
	v_add_f32_e32 v67, v71, v67
	v_cndmask_b32_e64 v65, v216, v65, s[22:23]
	v_cndmask_b32_e64 v66, v216, v66, s[24:25]
	v_cndmask_b32_e64 v67, v216, v67, s[26:27]
	v_exp_f32_e32 v202, v91
	v_exp_f32_e32 v203, v64
	v_exp_f32_e32 v204, v65
	v_exp_f32_e32 v205, v66
	v_exp_f32_e32 v230, v67
	v_cvt_pk_bf16_f32 v140, v148, v177
	v_cvt_pk_bf16_f32 v141, v179, v202
	v_cvt_pk_bf16_f32 v142, v203, v204
	v_cvt_pk_bf16_f32 v143, v205, v230
	ds_read2_b32 v[68:69], v175 offset0:16 offset1:17
	v_mfma_f32_32x32x16_bf16 v[32:47], v[84:87], v[140:143], v[32:47]
	ds_read_b128 v[154:157], v226 offset:6144
	ds_read_b128 v[64:67], v227 offset:4096
	ds_read2_b32 v[70:71], v175 offset0:18 offset1:19
	s_waitcnt lgkmcnt(0)
	v_add_f32_e32 v68, v72, v68
	v_cndmask_b32_e64 v72, v216, v68, s[6:7]
	v_add_f32_e32 v68, v73, v69
	v_cndmask_b32_e64 v73, v216, v68, s[30:31]
	v_mfma_f32_32x32x16_bf16 v[80:95], v[80:83], v[112:115], 0
	v_add_f32_e32 v68, v74, v70
	v_cndmask_b32_e64 v150, v216, v68, s[34:35]
	ds_read2_b32 v[68:69], v175 offset0:20 offset1:21
	v_add_f32_e32 v70, v75, v71
	v_cndmask_b32_e64 v75, v216, v70, s[36:37]
	v_mfma_f32_32x32x16_bf16 v[80:95], v[136:139], v[116:119], v[80:95]
	s_waitcnt lgkmcnt(0)
	v_add_f32_e32 v68, v76, v68
	v_cndmask_b32_e64 v76, v216, v68, s[38:39]
	v_add_f32_e32 v68, v77, v69
	v_cndmask_b32_e64 v69, v216, v68, s[40:41]
	v_exp_f32_e32 v198, v69
	ds_read2_b32 v[70:71], v175 offset0:22 offset1:23
	v_mfma_f32_32x32x16_bf16 v[80:95], v[132:135], v[120:123], v[80:95]
	v_exp_f32_e32 v74, v72
	v_exp_f32_e32 v72, v73
	v_readlane_b32 s8, v254, 43
	s_waitcnt lgkmcnt(0)
	v_add_f32_e32 v68, v78, v70
	v_cndmask_b32_e64 v77, v216, v68, s[42:43]
	v_add_f32_e32 v68, v79, v71
	v_cndmask_b32_e64 v71, v216, v68, s[44:45]
	v_mfma_f32_32x32x16_bf16 v[80:95], v[128:131], v[124:127], v[80:95]
	v_exp_f32_e32 v78, v76
	v_exp_f32_e32 v76, v77
	v_exp_f32_e32 v200, v71
	v_readlane_b32 s9, v254, 44
	v_exp_f32_e32 v68, v150
	s_nop 6
	ds_read2_b32 v[80:81], v159 offset0:16 offset1:17
	ds_read2_b32 v[82:83], v159 offset0:18 offset1:19
	v_exp_f32_e32 v70, v75
	v_mfma_f32_32x32x16_bf16 v[48:63], v[154:157], v[140:143], v[48:63]
	s_waitcnt lgkmcnt(0)
	v_add_f32_e32 v69, v88, v80
	v_add_f32_e32 v71, v89, v81
	v_add_f32_e32 v73, v90, v82
	v_cndmask_b32_e64 v77, v216, v73, s[48:49]
	ds_read2_b32 v[80:81], v159 offset0:20 offset1:21
	v_add_f32_e32 v73, v91, v83
	v_cndmask_b32_e64 v79, v216, v73, s[50:51]
	ds_read2_b32 v[82:83], v159 offset0:22 offset1:23
	s_waitcnt lgkmcnt(0)
	v_add_f32_e32 v73, v92, v80
	v_cndmask_b32_e64 v80, v216, v73, s[52:53]
	v_add_f32_e32 v73, v93, v81
	v_cndmask_b32_e64 v84, v216, v73, s[54:55]
	v_add_f32_e32 v73, v94, v82
	v_cndmask_b32_e64 v85, v216, v73, s[56:57]
	v_add_f32_e32 v73, v95, v83
	v_cndmask_b32_e64 v69, v216, v69, s[8:9]
	v_cndmask_b32_e64 v71, v216, v71, s[46:47]
	v_cndmask_b32_e64 v86, v216, v73, s[58:59]
	v_exp_f32_e32 v75, v69
	v_exp_f32_e32 v73, v71
	v_exp_f32_e32 v69, v77
	v_exp_f32_e32 v71, v79
	v_exp_f32_e32 v79, v80
	v_exp_f32_e32 v199, v84
	v_exp_f32_e32 v77, v85
	v_exp_f32_e32 v201, v86
	v_cvt_pk_bf16_f32 v80, v74, v72
	v_cvt_pk_bf16_f32 v81, v68, v70
	v_cvt_pk_bf16_f32 v82, v78, v198
	v_cvt_pk_bf16_f32 v83, v76, v200
	v_cvt_pk_bf16_f32 v154, v75, v73
	v_cvt_pk_bf16_f32 v155, v69, v71
	v_cvt_pk_bf16_f32 v156, v79, v199
	v_cvt_pk_bf16_f32 v157, v77, v201
	v_mfma_f32_32x32x16_bf16 v[32:47], v[64:67], v[80:83], v[32:47]
	s_cselect_b64 s[8:9], -1, 0
	s_and_b64 vcc, exec, s[8:9]
	v_mfma_f32_32x32x16_bf16 v[0:15], v[64:67], v[154:157], v[0:15]
	ds_read_b128 v[64:67], v227 offset:6144
	s_waitcnt vmcnt(0)
	ds_read_b128 v[140:143], v222 offset:8192
	s_waitcnt lgkmcnt(0)
	v_mfma_f32_32x32x16_bf16 v[48:63], v[64:67], v[80:83], v[48:63]
	ds_read_b128 v[136:139], v223 offset:8192
	ds_read_b128 v[128:131], v224 offset:8192
	ds_read_b128 v[132:135], v225 offset:8192
	ds_read_b128 v[92:95], v226 offset:12288
	ds_read_b128 v[88:91], v226 offset:14336
	ds_read_b128 v[84:87], v227 offset:12288
	ds_read_b128 v[80:83], v227 offset:14336
	v_mfma_f32_32x32x16_bf16 v[16:31], v[64:67], v[154:157], v[16:31]
	s_cbranch_vccnz .LBB0_1263
	s_mov_b32 m0, s33
	s_add_u32 s98, s32, 0x17610000
	s_addc_u32 s99, s100, 0
	global_load_lds_dwordx4 v231, s[98:99]
	s_add_i32 m0, s33, 0x400
	s_add_u32 s98, s32, 0x17611000
	s_addc_u32 s99, s100, 0
	global_load_lds_dwordx4 v232, s[98:99]
	s_add_i32 m0, s33, 0x800
	s_add_u32 s98, s32, 0x17614000
	s_addc_u32 s99, s100, 0
	global_load_lds_dwordx4 v231, s[98:99]
	s_add_i32 m0, s33, 0xc00
	s_add_u32 s98, s32, 0x17615000
	s_addc_u32 s99, s100, 0
	global_load_lds_dwordx4 v232, s[98:99]
	s_add_i32 m0, s33, 0x1000
	s_add_u32 s98, s32, 0x15600080
	s_addc_u32 s99, s100, 0
	global_load_lds_dwordx4 v233, s[98:99]
	s_add_i32 m0, s33, 0x1400
	s_add_u32 s98, s32, 0x15700080
	s_addc_u32 s99, s100, 0
	global_load_lds_dwordx4 v233, s[98:99]
	s_add_i32 m0, s33, 0x1800
	s_add_u32 s98, s32, 0x15800080
	s_addc_u32 s99, s100, 0
	global_load_lds_dwordx4 v233, s[98:99]
	s_add_i32 m0, s33, 0x1c00
	s_add_u32 s98, s32, 0x15900080
	s_addc_u32 s99, s100, 0
	global_load_lds_dwordx4 v233, s[98:99]
	s_branch .LBB0_1263
